# DIFF and SWA attention epilogues: gate / sub-LN weight loads issued once up front (were one load + vmcnt(0) per 4-feature group, behind the previous store)
# speedup vs baseline: 1.0085x; 1.0016x over previous
; DI unsigned pk2(float lo, float hi) { f32x2 v = {lo, hi}; b16x2 r = __builtin_convertvector(v, b16x2); return __builtin_bit_cast(unsigned, r); }
; DI float bflo(unsigned w) { return __uint_as_float(w << 16); }
; DI float bfhi(unsigned w) { return __uint_as_float(w & 0xffff0000u); }
; template <int MODE>
; DI void attn_item(const Params& p, int layer, int bh, int qb, char* lds) {
;     ...
;   const size_t trow = (size_t)b * S + q0w + l32;
;   const u16* grow = (const u16*)(p.ws + OFF_H) + trow * DIN + C_GATE + ocol;
;   u16* orow = (u16*)(p.ws + OFF_OB) + trow * DM + ocol;
;   float inv0 = 1.f / xchg_sum(l[0]);
;   if (MODE == 1) {
;     const float* lm = (const float*)(p.ws + OFF_LAM);
;     const float lam = lm[layer], post = lm[4 + layer];
;     const float inv1 = lam / xchg_sum(l[1]);
;     float ss = 0.f;
; #pragma unroll
;     for (int dt = 0; dt < 2; ++dt)
; #pragma unroll
;       for (int r = 0; r < 16; ++r) { float v = O[0][dt][r] * inv0 - O[NMAP - 1][dt][r] * inv1; O[0][dt][r] = v; ss += v * v; }
;     ss = xchg_sum(ss);
;     inv0 = rsqrtf(ss * (1.f / 64.f) + 1e-6f) * post;
;   }
; #pragma unroll
;   for (int dt = 0; dt < 2; ++dt)
; #pragma unroll
;     for (int g = 0; g < 4; ++g) {
;       const int d = 32 * dt + 8 * g + 4 * hh;
;       u32x2 gw = *(const u32x2*)(grow + d);
;       float v0 = O[0][dt][4 * g + 0] * inv0, v1 = O[0][dt][4 * g + 1] * inv0, v2 = O[0][dt][4 * g + 2] * inv0, v3 = O[0][dt][4 * g + 3] * inv0;
;       if (MODE == 1) { const float* sl = p.subln + layer * 64 + d; v0 *= sl[0]; v1 *= sl[1]; v2 *= sl[2]; v3 *= sl[3]; }
;       v0 *= bflo(gw[0]); v1 *= bfhi(gw[0]); v2 *= bflo(gw[1]); v3 *= bfhi(gw[1]);
;       u32x2 ow = {pk2(v0, v1), pk2(v2, v3)};
;     ...
;       if (MODE == PROBE_ZERO_MODE) { ow[0] = 0u; ow[1] = 0u; }
;     ...
;       *(u32x2*)(orow + d) = ow;
;     }
.LBB0_389:
	v_ashrrev_i32_e32 v187, 31, v186
	v_lshl_add_u64 v[0:1], v[186:187], 0, s[52:53]
	v_or_b32_e32 v0, v0, v222
	v_mov_b64_e32 v[2:3], s[34:35]
	v_mad_u64_u32 v[2:3], s[4:5], v0, s64, v[2:3]
	v_readlane_b32 s6, v254, 49
	v_mad_i32_i24 v3, v1, s64, v3
	s_mov_b64 s[4:5], 0x6058ec0
	v_lshlrev_b64 v[0:1], 11, v[0:1]
	v_readlane_b32 s7, v254, 50
	v_lshl_add_u64 v[2:3], v[2:3], 0, s[4:5]
	s_lshl_b32 s4, s63, 1
	v_lshl_add_u64 v[0:1], s[6:7], 0, v[0:1]
	s_mov_b32 s5, s53
	v_lshl_add_u64 v[8:9], v[0:1], 0, s[4:5]
	v_mov_b32_e32 v0, v231
	s_nop 1
	v_permlane32_swap_b32_e32 v231, v0
	v_add_f32_e32 v0, v231, v0
	s_add_i32 s52, s4, 0x500
	v_div_scale_f32 v1, s[4:5], v0, v0, 1.0
	v_rcp_f32_e32 v4, v1
	v_lshl_add_u64 v[6:7], v[2:3], 0, s[52:53]
	s_waitcnt lgkmcnt(0)
	s_barrier
	v_fma_f32 v10, -v1, v4, 1.0
	v_fmac_f32_e32 v4, v10, v4
	v_div_scale_f32 v10, vcc, 1.0, v0, 1.0
	v_mul_f32_e32 v11, v10, v4
	v_fma_f32 v12, -v1, v11, v10
	v_fmac_f32_e32 v11, v12, v4
	v_fma_f32 v1, -v1, v11, v10
	v_div_fmas_f32 v1, v1, v4, v11
	v_lshlrev_b32_e32 v4, 1, v189
	v_lshl_add_u64 v[2:3], v[2:3], 0, v[4:5]
	v_lshl_add_u64 v[2:3], v[2:3], 0, s[52:53]
	global_load_dwordx2 v[64:65], v[2:3], off
	global_load_dwordx2 v[66:67], v[2:3], off offset:16
	global_load_dwordx2 v[68:69], v[2:3], off offset:32
	global_load_dwordx2 v[70:71], v[2:3], off offset:48
	global_load_dwordx2 v[72:73], v[2:3], off offset:64
	global_load_dwordx2 v[74:75], v[2:3], off offset:80
	global_load_dwordx2 v[76:77], v[2:3], off offset:96
	global_load_dwordx2 v[78:79], v[2:3], off offset:112
	v_div_fixup_f32 v0, v1, v0, 1.0
	v_pk_mul_f32 v[10:11], v[32:33], v[0:1] op_sel_hi:[1,0]
	v_lshl_add_u64 v[6:7], v[6:7], 0, v[4:5]
	s_mov_b64 s[4:5], 0
	v_readlane_b32 s63, v255, 39
	s_waitcnt vmcnt(0)
	v_lshlrev_b32_e32 v12, 16, v64
	v_and_b32_e32 v13, 0xffff0000, v64
	v_pk_mul_f32 v[10:11], v[10:11], v[12:13]
	v_pk_mul_f32 v[12:13], v[34:35], v[0:1] op_sel_hi:[1,0]
	v_lshlrev_b32_e32 v2, 16, v65
	v_and_b32_e32 v3, 0xffff0000, v65
	v_pk_mul_f32 v[2:3], v[12:13], v[2:3]
	v_cvt_pk_bf16_f32 v10, v10, v11
	v_cvt_pk_bf16_f32 v11, v2, v3
	v_lshl_add_u64 v[2:3], v[8:9], 0, v[4:5]
	global_store_dwordx2 v[2:3], v[10:11], off offset:1280
	v_pk_mul_f32 v[10:11], v[36:37], v[0:1] op_sel_hi:[1,0]
	v_lshlrev_b32_e32 v12, 16, v66
	v_and_b32_e32 v13, 0xffff0000, v66
	v_pk_mul_f32 v[10:11], v[10:11], v[12:13]
	v_pk_mul_f32 v[12:13], v[38:39], v[0:1] op_sel_hi:[1,0]
	v_lshlrev_b32_e32 v8, 16, v67
	v_and_b32_e32 v9, 0xffff0000, v67
	v_pk_mul_f32 v[8:9], v[12:13], v[8:9]
	v_cvt_pk_bf16_f32 v10, v10, v11
	v_cvt_pk_bf16_f32 v11, v8, v9
	global_store_dwordx2 v[2:3], v[10:11], off offset:1296
	v_pk_mul_f32 v[10:11], v[40:41], v[0:1] op_sel_hi:[1,0]
	v_lshlrev_b32_e32 v12, 16, v68
	v_and_b32_e32 v13, 0xffff0000, v68
	v_pk_mul_f32 v[10:11], v[10:11], v[12:13]
	v_pk_mul_f32 v[12:13], v[42:43], v[0:1] op_sel_hi:[1,0]
	v_lshlrev_b32_e32 v8, 16, v69
	v_and_b32_e32 v9, 0xffff0000, v69
	v_pk_mul_f32 v[8:9], v[12:13], v[8:9]
	v_cvt_pk_bf16_f32 v10, v10, v11
	v_cvt_pk_bf16_f32 v11, v8, v9
	global_store_dwordx2 v[2:3], v[10:11], off offset:1312
	v_pk_mul_f32 v[10:11], v[44:45], v[0:1] op_sel_hi:[1,0]
	v_lshlrev_b32_e32 v12, 16, v70
	v_and_b32_e32 v13, 0xffff0000, v70
	v_pk_mul_f32 v[10:11], v[10:11], v[12:13]
	v_pk_mul_f32 v[12:13], v[46:47], v[0:1] op_sel_hi:[1,0]
	v_lshlrev_b32_e32 v8, 16, v71
	v_and_b32_e32 v9, 0xffff0000, v71
	v_pk_mul_f32 v[8:9], v[12:13], v[8:9]
	v_cvt_pk_bf16_f32 v10, v10, v11
	v_cvt_pk_bf16_f32 v11, v8, v9
	global_store_dwordx2 v[2:3], v[10:11], off offset:1328
	v_pk_mul_f32 v[10:11], v[16:17], v[0:1] op_sel_hi:[1,0]
	v_lshlrev_b32_e32 v12, 16, v72
	v_and_b32_e32 v13, 0xffff0000, v72
	v_pk_mul_f32 v[10:11], v[10:11], v[12:13]
	v_pk_mul_f32 v[12:13], v[18:19], v[0:1] op_sel_hi:[1,0]
	v_lshlrev_b32_e32 v8, 16, v73
	v_and_b32_e32 v9, 0xffff0000, v73
	v_pk_mul_f32 v[8:9], v[12:13], v[8:9]
	v_cvt_pk_bf16_f32 v10, v10, v11
	v_cvt_pk_bf16_f32 v11, v8, v9
	global_store_dwordx2 v[2:3], v[10:11], off offset:1344
	v_pk_mul_f32 v[10:11], v[20:21], v[0:1] op_sel_hi:[1,0]
	v_lshlrev_b32_e32 v12, 16, v74
	v_and_b32_e32 v13, 0xffff0000, v74
	v_pk_mul_f32 v[10:11], v[10:11], v[12:13]
	v_pk_mul_f32 v[12:13], v[22:23], v[0:1] op_sel_hi:[1,0]
	v_lshlrev_b32_e32 v8, 16, v75
	v_and_b32_e32 v9, 0xffff0000, v75
	v_pk_mul_f32 v[8:9], v[12:13], v[8:9]
	v_cvt_pk_bf16_f32 v10, v10, v11
	v_cvt_pk_bf16_f32 v11, v8, v9
	global_store_dwordx2 v[2:3], v[10:11], off offset:1360
	v_pk_mul_f32 v[10:11], v[24:25], v[0:1] op_sel_hi:[1,0]
	v_lshlrev_b32_e32 v12, 16, v76
	v_and_b32_e32 v13, 0xffff0000, v76
	v_pk_mul_f32 v[10:11], v[10:11], v[12:13]
	v_pk_mul_f32 v[12:13], v[26:27], v[0:1] op_sel_hi:[1,0]
	v_lshlrev_b32_e32 v8, 16, v77
	v_and_b32_e32 v9, 0xffff0000, v77
	v_pk_mul_f32 v[8:9], v[12:13], v[8:9]
	v_cvt_pk_bf16_f32 v10, v10, v11
	v_cvt_pk_bf16_f32 v11, v8, v9
	global_store_dwordx2 v[2:3], v[10:11], off offset:1376
	v_pk_mul_f32 v[8:9], v[28:29], v[0:1] op_sel_hi:[1,0]
	v_pk_mul_f32 v[0:1], v[30:31], v[0:1] op_sel_hi:[1,0]
	v_lshlrev_b32_e32 v10, 16, v78
	v_and_b32_e32 v11, 0xffff0000, v78
	v_lshlrev_b32_e32 v6, 16, v79
	v_and_b32_e32 v7, 0xffff0000, v79
	v_pk_mul_f32 v[8:9], v[8:9], v[10:11]
	v_pk_mul_f32 v[0:1], v[0:1], v[6:7]
	v_cvt_pk_bf16_f32 v6, v8, v9
	v_cvt_pk_bf16_f32 v7, v0, v1
	global_store_dwordx2 v[2:3], v[6:7], off offset:1392

; template <int MODE>
; DI void attn_item(const Params& p, int layer, int bh, int qb, char* lds) {
;     ...
;   const size_t trow = (size_t)b * S + q0w + l32;
;   const u16* grow = (const u16*)(p.ws + OFF_H) + trow * DIN + C_GATE + ocol;
;   u16* orow = (u16*)(p.ws + OFF_OB) + trow * DM + ocol;
;   float inv0 = 1.f / xchg_sum(l[0]);
;   if (MODE == 1) {
;     const float* lm = (const float*)(p.ws + OFF_LAM);
;     const float lam = lm[layer], post = lm[4 + layer];
;     const float inv1 = lam / xchg_sum(l[1]);
;     float ss = 0.f;
; #pragma unroll
;     for (int dt = 0; dt < 2; ++dt)
; #pragma unroll
;       for (int r = 0; r < 16; ++r) { float v = O[0][dt][r] * inv0 - O[NMAP - 1][dt][r] * inv1; O[0][dt][r] = v; ss += v * v; }
;     ss = xchg_sum(ss);
;     inv0 = rsqrtf(ss * (1.f / 64.f) + 1e-6f) * post;
;   }
; #pragma unroll
;   for (int dt = 0; dt < 2; ++dt)
; #pragma unroll
;     for (int g = 0; g < 4; ++g) {
;       const int d = 32 * dt + 8 * g + 4 * hh;
;       u32x2 gw = *(const u32x2*)(grow + d);
;       float v0 = O[0][dt][4 * g + 0] * inv0, v1 = O[0][dt][4 * g + 1] * inv0, v2 = O[0][dt][4 * g + 2] * inv0, v3 = O[0][dt][4 * g + 3] * inv0;
;       if (MODE == 1) { const float* sl = p.subln + layer * 64 + d; v0 *= sl[0]; v1 *= sl[1]; v2 *= sl[2]; v3 *= sl[3]; }
.LBB0_505:
	v_ashrrev_i32_e32 v169, 31, v168
	v_lshl_add_u64 v[0:1], v[168:169], 0, s[52:53]
	v_or_b32_e32 v0, v0, v203
	v_mov_b64_e32 v[2:3], s[34:35]
	v_mad_u64_u32 v[2:3], s[4:5], v0, s64, v[2:3]
	v_mov_b32_e32 v4, v170
	v_readlane_b32 s4, v254, 49
	s_nop 0
	v_permlane32_swap_b32_e32 v170, v4
	v_mad_i32_i24 v3, v1, s64, v3
	v_lshlrev_b64 v[0:1], 11, v[0:1]
	v_readlane_b32 s5, v254, 50
	v_add_f32_e32 v4, v170, v4
	s_waitcnt lgkmcnt(0)
	v_lshl_add_u64 v[0:1], s[4:5], 0, v[0:1]
	v_div_scale_f32 v6, s[4:5], v4, v4, 1.0
	v_rcp_f32_e32 v7, v6
	s_barrier
	v_fma_f32 v72, -v6, v7, 1.0
	v_fmac_f32_e32 v7, v72, v7
	v_div_scale_f32 v72, vcc, 1.0, v4, 1.0
	v_mul_f32_e32 v73, v72, v7
	v_fma_f32 v74, -v6, v73, v72
	v_fmac_f32_e32 v73, v74, v7
	v_fma_f32 v6, -v6, v73, v72
	v_div_fmas_f32 v6, v6, v7, v73
	v_div_fixup_f32 v72, v6, v4, 1.0
	global_load_dword v4, v5, s[72:73]
	global_load_dword v75, v5, s[72:73] offset:16
	v_mov_b32_e32 v6, v171
	s_nop 1
	v_permlane32_swap_b32_e32 v171, v6
	v_add_f32_e32 v6, v171, v6
	s_waitcnt vmcnt(1)
	v_div_scale_f32 v7, s[4:5], v6, v6, v4
	v_rcp_f32_e32 v73, v7
	s_mov_b64 s[4:5], 0x6058ec0
	v_lshl_add_u64 v[2:3], v[2:3], 0, s[4:5]
	s_lshl_b32 s4, s49, 1
	v_fma_f32 v74, -v7, v73, 1.0
	v_fmac_f32_e32 v73, v74, v73
	v_div_scale_f32 v74, vcc, v4, v6, v4
	v_mul_f32_e32 v76, v74, v73
	v_fma_f32 v77, -v7, v76, v74
	v_fmac_f32_e32 v76, v77, v73
	v_fma_f32 v7, -v7, v76, v74
	v_div_fmas_f32 v7, v7, v73, v76
	v_div_fixup_f32 v74, v7, v6, v4
	s_mov_b32 s5, s53
	v_lshlrev_b32_e32 v4, 1, v202
	s_add_i32 s52, s4, 0x300
	v_lshl_add_u64 v[6:7], v[0:1], 0, s[4:5]
	v_lshl_add_u64 v[0:1], v[2:3], 0, v[4:5]
	v_lshl_add_u64 v[0:1], v[0:1], 0, s[52:53]
	global_load_dwordx2 v[88:89], v[0:1], off
	global_load_dwordx2 v[90:91], v[0:1], off offset:16
	global_load_dwordx2 v[92:93], v[0:1], off offset:32
	global_load_dwordx2 v[94:95], v[0:1], off offset:48
	global_load_dwordx2 v[96:97], v[0:1], off offset:64
	global_load_dwordx2 v[98:99], v[0:1], off offset:80
	global_load_dwordx2 v[100:101], v[0:1], off offset:96
	global_load_dwordx2 v[102:103], v[0:1], off offset:112
	v_lshlrev_b32_e32 v73, 2, v202
	s_waitcnt vmcnt(8)
	v_pk_mul_f32 v[0:1], v[42:43], v[74:75] op_sel_hi:[1,0]
	v_pk_mul_f32 v[40:41], v[40:41], v[74:75] op_sel_hi:[1,0]
	v_pk_fma_f32 v[42:43], v[58:59], v[72:73], v[0:1] op_sel_hi:[1,0,1] neg_lo:[0,0,1] neg_hi:[0,0,1]
	v_pk_fma_f32 v[58:59], v[56:57], v[72:73], v[40:41] op_sel_hi:[1,0,1] neg_lo:[0,0,1] neg_hi:[0,0,1]
	v_lshl_add_u64 v[78:79], v[2:3], 0, s[52:53]
	v_mul_f32_e32 v40, v59, v59
	v_pk_fma_f32 v[40:41], v[58:59], v[58:59], v[40:41] op_sel_hi:[1,1,0]
	v_pk_mul_f32 v[44:45], v[44:45], v[74:75] op_sel_hi:[1,0]
	v_pk_fma_f32 v[40:41], v[42:43], v[42:43], v[40:41]
	v_pk_fma_f32 v[60:61], v[60:61], v[72:73], v[44:45] op_sel_hi:[1,0,1] neg_lo:[0,0,1] neg_hi:[0,0,1]
	global_load_dwordx4 v[132:135], v73, s[78:79]
	global_load_dwordx4 v[136:139], v73, s[78:79] offset:32
	global_load_dwordx4 v[140:143], v73, s[78:79] offset:64
	global_load_dwordx4 v[144:147], v73, s[78:79] offset:96
	global_load_dwordx4 v[148:151], v73, s[78:79] offset:128
	global_load_dwordx4 v[152:155], v73, s[78:79] offset:160
	global_load_dwordx4 v[156:159], v73, s[78:79] offset:192
	global_load_dwordx4 v[160:163], v73, s[78:79] offset:224
	v_lshl_add_u64 v[6:7], v[6:7], 0, v[4:5]
	v_pk_mul_f32 v[46:47], v[46:47], v[74:75] op_sel_hi:[1,0]
	v_pk_mul_f32 v[48:49], v[48:49], v[74:75] op_sel_hi:[1,0]
	v_pk_fma_f32 v[62:63], v[62:63], v[72:73], v[46:47] op_sel_hi:[1,0,1] neg_lo:[0,0,1] neg_hi:[0,0,1]
	v_pk_fma_f32 v[64:65], v[64:65], v[72:73], v[48:49] op_sel_hi:[1,0,1] neg_lo:[0,0,1] neg_hi:[0,0,1]
	v_pk_mul_f32 v[50:51], v[50:51], v[74:75] op_sel_hi:[1,0]
	v_pk_mul_f32 v[52:53], v[52:53], v[74:75] op_sel_hi:[1,0]
	v_pk_fma_f32 v[66:67], v[66:67], v[72:73], v[50:51] op_sel_hi:[1,0,1] neg_lo:[0,0,1] neg_hi:[0,0,1]
	v_pk_fma_f32 v[68:69], v[68:69], v[72:73], v[52:53] op_sel_hi:[1,0,1] neg_lo:[0,0,1] neg_hi:[0,0,1]
	v_pk_mul_f32 v[54:55], v[54:55], v[74:75] op_sel_hi:[1,0]
	v_pk_mul_f32 v[8:9], v[8:9], v[74:75] op_sel_hi:[1,0]
	v_pk_fma_f32 v[70:71], v[70:71], v[72:73], v[54:55] op_sel_hi:[1,0,1] neg_lo:[0,0,1] neg_hi:[0,0,1]
	v_pk_fma_f32 v[24:25], v[24:25], v[72:73], v[8:9] op_sel_hi:[1,0,1] neg_lo:[0,0,1] neg_hi:[0,0,1]
	v_pk_mul_f32 v[10:11], v[10:11], v[74:75] op_sel_hi:[1,0]
	v_pk_mul_f32 v[12:13], v[12:13], v[74:75] op_sel_hi:[1,0]
	v_pk_fma_f32 v[10:11], v[26:27], v[72:73], v[10:11] op_sel_hi:[1,0,1] neg_lo:[0,0,1] neg_hi:[0,0,1]
	v_pk_fma_f32 v[28:29], v[28:29], v[72:73], v[12:13] op_sel_hi:[1,0,1] neg_lo:[0,0,1] neg_hi:[0,0,1]
	v_pk_mul_f32 v[14:15], v[14:15], v[74:75] op_sel_hi:[1,0]
	v_pk_mul_f32 v[12:13], v[18:19], v[74:75] op_sel_hi:[1,0]
	v_pk_fma_f32 v[26:27], v[30:31], v[72:73], v[14:15] op_sel_hi:[1,0,1] neg_lo:[0,0,1] neg_hi:[0,0,1]
	v_pk_fma_f32 v[14:15], v[34:35], v[72:73], v[12:13] op_sel_hi:[1,0,1] neg_lo:[0,0,1] neg_hi:[0,0,1]
	v_pk_mul_f32 v[12:13], v[16:17], v[74:75] op_sel_hi:[1,0]
	s_nop 0
	v_pk_fma_f32 v[16:17], v[32:33], v[72:73], v[12:13] op_sel_hi:[1,0,1] neg_lo:[0,0,1] neg_hi:[0,0,1]
	v_pk_mul_f32 v[12:13], v[20:21], v[74:75] op_sel_hi:[1,0]
	s_waitcnt vmcnt(15)
; DI unsigned pk2(float lo, float hi) { f32x2 v = {lo, hi}; b16x2 r = __builtin_convertvector(v, b16x2); return __builtin_bit_cast(unsigned, r); }
; DI float bflo(unsigned w) { return __uint_as_float(w << 16); }
; DI float bfhi(unsigned w) { return __uint_as_float(w & 0xffff0000u); }
; template <int MODE>
; DI void attn_item(const Params& p, int layer, int bh, int qb, char* lds) {
;     ...
;     float ss = 0.f;
; #pragma unroll
;     for (int dt = 0; dt < 2; ++dt)
; #pragma unroll
;       for (int r = 0; r < 16; ++r) { float v = O[0][dt][r] * inv0 - O[NMAP - 1][dt][r] * inv1; O[0][dt][r] = v; ss += v * v; }
;     ss = xchg_sum(ss);
;     inv0 = rsqrtf(ss * (1.f / 64.f) + 1e-6f) * post;
;   }
; #pragma unroll
;   for (int dt = 0; dt < 2; ++dt)
; #pragma unroll
;     for (int g = 0; g < 4; ++g) {
;       const int d = 32 * dt + 8 * g + 4 * hh;
;       u32x2 gw = *(const u32x2*)(grow + d);
;       float v0 = O[0][dt][4 * g + 0] * inv0, v1 = O[0][dt][4 * g + 1] * inv0, v2 = O[0][dt][4 * g + 2] * inv0, v3 = O[0][dt][4 * g + 3] * inv0;
;       if (MODE == 1) { const float* sl = p.subln + layer * 64 + d; v0 *= sl[0]; v1 *= sl[1]; v2 *= sl[2]; v3 *= sl[3]; }
;       v0 *= bflo(gw[0]); v1 *= bfhi(gw[0]); v2 *= bflo(gw[1]); v3 *= bfhi(gw[1]);
;       u32x2 ow = {pk2(v0, v1), pk2(v2, v3)};
;     ...
;       if (MODE == PROBE_ZERO_MODE) { ow[0] = 0u; ow[1] = 0u; }
;     ...
;       *(u32x2*)(orow + d) = ow;
;     }
	v_lshlrev_b32_e32 v56, 16, v88
	v_and_b32_e32 v57, 0xffff0000, v88
	v_mul_f32_e32 v76, v43, v43
	v_pk_add_f32 v[80:81], v[76:77], v[40:41] op_sel_hi:[0,1]
	v_lshl_add_u64 v[40:41], v[78:79], 0, v[4:5]
	v_pk_fma_f32 v[44:45], v[60:61], v[60:61], v[80:81]
	v_mul_f32_e32 v4, v61, v61
	v_pk_add_f32 v[46:47], v[4:5], v[44:45] op_sel_hi:[0,1]
	v_pk_fma_f32 v[46:47], v[62:63], v[62:63], v[46:47]
	v_mul_f32_e32 v4, v63, v63
	v_pk_add_f32 v[80:81], v[4:5], v[46:47] op_sel_hi:[0,1]
	v_pk_fma_f32 v[48:49], v[64:65], v[64:65], v[80:81]
	v_mul_f32_e32 v4, v65, v65
	v_pk_add_f32 v[50:51], v[4:5], v[48:49] op_sel_hi:[0,1]
	v_pk_fma_f32 v[50:51], v[66:67], v[66:67], v[50:51]
	v_mul_f32_e32 v4, v67, v67
	v_pk_add_f32 v[80:81], v[4:5], v[50:51] op_sel_hi:[0,1]
	v_pk_fma_f32 v[52:53], v[68:69], v[68:69], v[80:81]
	v_mul_f32_e32 v4, v69, v69
	v_pk_add_f32 v[54:55], v[4:5], v[52:53] op_sel_hi:[0,1]
	v_pk_fma_f32 v[54:55], v[70:71], v[70:71], v[54:55]
	v_mul_f32_e32 v4, v71, v71
	v_pk_add_f32 v[80:81], v[4:5], v[54:55] op_sel_hi:[0,1]
	v_pk_fma_f32 v[8:9], v[24:25], v[24:25], v[80:81]
	v_mul_f32_e32 v4, v25, v25
	v_pk_add_f32 v[8:9], v[4:5], v[8:9] op_sel_hi:[0,1]
	v_pk_fma_f32 v[8:9], v[10:11], v[10:11], v[8:9]
	v_mul_f32_e32 v4, v11, v11
	v_pk_add_f32 v[8:9], v[4:5], v[8:9] op_sel_hi:[0,1]
	v_pk_fma_f32 v[8:9], v[28:29], v[28:29], v[8:9]
	v_mul_f32_e32 v4, v29, v29
	v_pk_add_f32 v[8:9], v[4:5], v[8:9] op_sel_hi:[0,1]
	v_pk_fma_f32 v[8:9], v[26:27], v[26:27], v[8:9]
	v_mul_f32_e32 v4, v27, v27
	v_pk_add_f32 v[8:9], v[4:5], v[8:9] op_sel_hi:[0,1]
	v_pk_fma_f32 v[8:9], v[16:17], v[16:17], v[8:9]
	v_mul_f32_e32 v4, v17, v17
	v_pk_add_f32 v[8:9], v[4:5], v[8:9] op_sel_hi:[0,1]
	v_pk_fma_f32 v[8:9], v[14:15], v[14:15], v[8:9]
	v_mul_f32_e32 v4, v15, v15
	v_pk_add_f32 v[18:19], v[4:5], v[8:9] op_sel_hi:[0,1]
	v_pk_fma_f32 v[12:13], v[36:37], v[72:73], v[12:13] op_sel_hi:[1,0,1] neg_lo:[0,0,1] neg_hi:[0,0,1]
	v_pk_mul_f32 v[8:9], v[22:23], v[74:75] op_sel_hi:[1,0]
	v_pk_fma_f32 v[18:19], v[12:13], v[12:13], v[18:19]
	v_mul_f32_e32 v4, v13, v13
	v_pk_fma_f32 v[8:9], v[38:39], v[72:73], v[8:9] op_sel_hi:[1,0,1] neg_lo:[0,0,1] neg_hi:[0,0,1]
	v_pk_add_f32 v[18:19], v[4:5], v[18:19] op_sel_hi:[0,1]
	v_pk_fma_f32 v[18:19], v[8:9], v[8:9], v[18:19]
	v_mul_f32_e32 v4, v9, v9
	v_pk_add_f32 v[18:19], v[4:5], v[18:19] op_sel_hi:[0,1]
	v_mov_b32_e32 v4, v18
	s_nop 1
	v_permlane32_swap_b32_e32 v18, v4
	v_add_f32_e32 v4, v18, v4
	v_mov_b32_e32 v18, 0x358637bd
	v_fmamk_f32 v4, v4, 0x3c800000, v18
	v_cmp_gt_f32_e32 vcc, s65, v4
	v_mul_f32_e32 v18, 0x4b800000, v4
	v_lshlrev_b32_e32 v76, 16, v89
	v_cndmask_b32_e32 v4, v4, v18, vcc
	v_rsq_f32_e32 v4, v4
	v_and_b32_e32 v77, 0xffff0000, v89
	v_mul_f32_e32 v18, 0x45800000, v4
	v_cndmask_b32_e32 v4, v4, v18, vcc
	v_mul_f32_e32 v4, v75, v4
	v_pk_mul_f32 v[18:19], v[58:59], v[4:5] op_sel_hi:[1,0]
	v_pk_mul_f32 v[20:21], v[42:43], v[4:5] op_sel_hi:[1,0]
	s_waitcnt vmcnt(7)
	v_pk_mul_f32 v[0:1], v[132:133], v[18:19]
	v_pk_mul_f32 v[2:3], v[134:135], v[20:21]
	v_pk_mul_f32 v[0:1], v[0:1], v[56:57]
	v_pk_mul_f32 v[2:3], v[2:3], v[76:77]
	v_cvt_pk_bf16_f32 v0, v0, v1
	v_cvt_pk_bf16_f32 v1, v2, v3
	v_pk_mul_f32 v[18:19], v[60:61], v[4:5] op_sel_hi:[1,0]
	v_pk_mul_f32 v[20:21], v[62:63], v[4:5] op_sel_hi:[1,0]
	v_pk_mul_f32 v[10:11], v[10:11], v[4:5] op_sel_hi:[1,0]
	v_pk_mul_f32 v[16:17], v[16:17], v[4:5] op_sel_hi:[1,0]
	v_pk_mul_f32 v[14:15], v[14:15], v[4:5] op_sel_hi:[1,0]
	v_pk_mul_f32 v[12:13], v[12:13], v[4:5] op_sel_hi:[1,0]
	v_pk_mul_f32 v[8:9], v[8:9], v[4:5] op_sel_hi:[1,0]
	s_waitcnt vmcnt(0)
	v_lshlrev_b32_e32 v44, 16, v90
	v_and_b32_e32 v45, 0xffff0000, v90
	v_lshlrev_b32_e32 v46, 16, v91
	v_and_b32_e32 v47, 0xffff0000, v91
	s_waitcnt vmcnt(0)
	v_lshlrev_b32_e32 v48, 16, v92
	v_and_b32_e32 v49, 0xffff0000, v92
	v_lshlrev_b32_e32 v50, 16, v93
	v_and_b32_e32 v51, 0xffff0000, v93
	s_waitcnt vmcnt(0)
	v_lshlrev_b32_e32 v52, 16, v94
	global_store_dwordx2 v[6:7], v[0:1], off offset:768
	v_and_b32_e32 v53, 0xffff0000, v94
	v_lshlrev_b32_e32 v54, 16, v95
	v_and_b32_e32 v55, 0xffff0000, v95
	v_pk_mul_f32 v[0:1], v[136:137], v[18:19]
	v_pk_mul_f32 v[2:3], v[138:139], v[20:21]
	v_pk_mul_f32 v[0:1], v[0:1], v[44:45]
	v_pk_mul_f32 v[2:3], v[2:3], v[46:47]
	v_cvt_pk_bf16_f32 v0, v0, v1
	v_cvt_pk_bf16_f32 v1, v2, v3
	global_store_dwordx2 v[6:7], v[0:1], off offset:784
	v_pk_mul_f32 v[18:19], v[64:65], v[4:5] op_sel_hi:[1,0]
	v_pk_mul_f32 v[20:21], v[66:67], v[4:5] op_sel_hi:[1,0]
	v_pk_mul_f32 v[0:1], v[18:19], v[140:141]
	v_pk_mul_f32 v[2:3], v[20:21], v[142:143]
	v_pk_mul_f32 v[0:1], v[0:1], v[48:49]
	v_pk_mul_f32 v[2:3], v[2:3], v[50:51]
	v_cvt_pk_bf16_f32 v0, v0, v1
	v_cvt_pk_bf16_f32 v1, v2, v3
	global_store_dwordx2 v[6:7], v[0:1], off offset:800
	v_pk_mul_f32 v[18:19], v[68:69], v[4:5] op_sel_hi:[1,0]
	v_pk_mul_f32 v[20:21], v[70:71], v[4:5] op_sel_hi:[1,0]
	v_pk_mul_f32 v[0:1], v[18:19], v[144:145]
	v_pk_mul_f32 v[2:3], v[20:21], v[146:147]
	v_pk_mul_f32 v[0:1], v[0:1], v[52:53]
	v_pk_mul_f32 v[2:3], v[2:3], v[54:55]
	v_cvt_pk_bf16_f32 v0, v0, v1
	v_cvt_pk_bf16_f32 v1, v2, v3
	global_store_dwordx2 v[6:7], v[0:1], off offset:816
	v_pk_mul_f32 v[20:21], v[24:25], v[4:5] op_sel_hi:[1,0]
	v_pk_mul_f32 v[0:1], v[20:21], v[148:149]
	v_pk_mul_f32 v[2:3], v[10:11], v[150:151]
	v_lshlrev_b32_e32 v10, 16, v96
	v_and_b32_e32 v11, 0xffff0000, v96
	v_pk_mul_f32 v[0:1], v[0:1], v[10:11]
	v_lshlrev_b32_e32 v10, 16, v97
	v_and_b32_e32 v11, 0xffff0000, v97
	v_pk_mul_f32 v[2:3], v[2:3], v[10:11]
	v_cvt_pk_bf16_f32 v0, v0, v1
	v_cvt_pk_bf16_f32 v1, v2, v3
	global_store_dwordx2 v[6:7], v[0:1], off offset:832
	v_pk_mul_f32 v[18:19], v[28:29], v[4:5] op_sel_hi:[1,0]
	v_pk_mul_f32 v[20:21], v[26:27], v[4:5] op_sel_hi:[1,0]
	v_pk_mul_f32 v[0:1], v[18:19], v[152:153]
	v_pk_mul_f32 v[2:3], v[20:21], v[154:155]
	v_lshlrev_b32_e32 v18, 16, v98
	v_and_b32_e32 v19, 0xffff0000, v98
	v_lshlrev_b32_e32 v10, 16, v99
	v_and_b32_e32 v11, 0xffff0000, v99
	v_pk_mul_f32 v[0:1], v[0:1], v[18:19]
	v_pk_mul_f32 v[2:3], v[2:3], v[10:11]
	v_cvt_pk_bf16_f32 v0, v0, v1
	v_cvt_pk_bf16_f32 v1, v2, v3
	global_store_dwordx2 v[6:7], v[0:1], off offset:848
	s_nop 0
	v_pk_mul_f32 v[0:1], v[16:17], v[156:157]
	v_pk_mul_f32 v[2:3], v[14:15], v[158:159]
	v_lshlrev_b32_e32 v14, 16, v100
	v_and_b32_e32 v15, 0xffff0000, v100
	v_lshlrev_b32_e32 v10, 16, v101
	v_and_b32_e32 v11, 0xffff0000, v101
	v_pk_mul_f32 v[0:1], v[0:1], v[14:15]
	v_pk_mul_f32 v[2:3], v[2:3], v[10:11]
	v_cvt_pk_bf16_f32 v0, v0, v1
	v_cvt_pk_bf16_f32 v1, v2, v3
	global_store_dwordx2 v[6:7], v[0:1], off offset:864
	s_nop 0
	v_pk_mul_f32 v[0:1], v[12:13], v[160:161]
	v_pk_mul_f32 v[2:3], v[8:9], v[162:163]
	v_lshlrev_b32_e32 v8, 16, v102
	v_and_b32_e32 v9, 0xffff0000, v102
	v_pk_mul_f32 v[0:1], v[0:1], v[8:9]
	v_lshlrev_b32_e32 v8, 16, v103
	v_and_b32_e32 v9, 0xffff0000, v103
	v_pk_mul_f32 v[2:3], v[2:3], v[8:9]
	v_cvt_pk_bf16_f32 v0, v0, v1
	v_cvt_pk_bf16_f32 v1, v2, v3
	global_store_dwordx2 v[6:7], v[0:1], off offset:880
	s_cbranch_execnz .LBB0_321
	s_branch .LBB0_403
